# sel fast steps: barrier moved to mid-block (after last V read), block-b V frags into freed K regs
# speedup vs baseline: 1.0112x; 1.0018x over previous
.Latt1a_entry:
	s_lshr_b32 s6, s9, 2
	s_and_b32 s6, s6, 0x3ffffff8
	s_waitcnt lgkmcnt(0)
	v_add3_u32 v251, s1, v205, v204
	v_add_u32_e32 v16, s6, v209
	s_add_i32 s1, s1, s0
	ds_read_b128 v[50:53], v251
	ds_read_b128 v[54:57], v251 offset:32
	ds_read_b128 v[58:61], v251 offset:64
	ds_read_b128 v[62:65], v251 offset:96
	ds_read_b128 v[66:69], v251 offset:4608
	ds_read_b128 v[70:73], v251 offset:4640
	ds_read_b128 v[74:77], v251 offset:4672
	ds_read_b128 v[78:81], v251 offset:4704
	ds_read_b64 v[16:17], v16
	v_add3_u32 v250, s1, v242, v244
	s_waitcnt lgkmcnt(8)
	v_mfma_f32_32x32x16_bf16 v[146:161], v[50:53], v[114:117], 0
	ds_read_b64_tr_b16 v[212:213], v250 offset:36864
	ds_read_b64_tr_b16 v[214:215], v250 offset:38400
	s_waitcnt lgkmcnt(9)
	v_mfma_f32_32x32x16_bf16 v[146:161], v[54:57], v[118:121], v[146:161]
	ds_read_b64_tr_b16 v[216:217], v250 offset:36928
	ds_read_b64_tr_b16 v[218:219], v250 offset:38464
	s_waitcnt lgkmcnt(10)
	v_mfma_f32_32x32x16_bf16 v[146:161], v[58:61], v[122:125], v[146:161]
	ds_read_b64_tr_b16 v[220:221], v250 offset:39936
	ds_read_b64_tr_b16 v[222:223], v250 offset:41472
	s_waitcnt lgkmcnt(11)
	v_mfma_f32_32x32x16_bf16 v[146:161], v[62:65], v[126:129], v[146:161]
	ds_read_b64_tr_b16 v[224:225], v250 offset:40000
	ds_read_b64_tr_b16 v[226:227], v250 offset:41536
	s_waitcnt lgkmcnt(8)
	v_and_b32_e32 v16, s28, v16
	v_and_b32_e32 v17, s29, v17
	v_cmp_eq_u64_e32 vcc, 0, v[16:17]
	s_nop 2
	v_mfma_f32_32x32x16_bf16 v[162:177], v[66:69], v[114:117], 0
	ds_read_b64_tr_b16 v[228:229], v250 offset:43008
	ds_read_b64_tr_b16 v[230:231], v250 offset:44544
	v_exp_f32_e32 v8, v146
	v_exp_f32_e32 v9, v147
	v_exp_f32_e32 v10, v148
	v_exp_f32_e32 v11, v149
	v_exp_f32_e32 v12, v150
	v_exp_f32_e32 v13, v151
	v_exp_f32_e32 v14, v152
	v_exp_f32_e32 v15, v153
	v_cvt_pk_bf16_f32 v178, v8, v9
	v_cvt_pk_bf16_f32 v179, v10, v11
	v_cvt_pk_bf16_f32 v180, v12, v13
	v_mfma_f32_32x32x16_bf16 v[162:177], v[70:73], v[118:121], v[162:177]
	ds_read_b64_tr_b16 v[232:233], v250 offset:43072
	ds_read_b64_tr_b16 v[234:235], v250 offset:44608
	v_cvt_pk_bf16_f32 v181, v14, v15
	v_add_f32_e32 v8, v8, v9
	v_add_f32_e32 v10, v10, v11
	v_add_f32_e32 v12, v12, v13
	v_add_f32_e32 v14, v14, v15
	v_add_f32_e32 v8, v8, v10
	v_add_f32_e32 v12, v12, v14
	v_add_f32_e32 v202, v8, v12
	v_cndmask_b32_e64 v178, v178, 0, vcc
	v_cndmask_b32_e64 v179, v179, 0, vcc
	v_cndmask_b32_e64 v180, v180, 0, vcc
	v_cndmask_b32_e64 v181, v181, 0, vcc
	v_mfma_f32_32x32x16_bf16 v[162:177], v[74:77], v[122:125], v[162:177]
	ds_read_b64_tr_b16 v[236:237], v250 offset:46080
	ds_read_b64_tr_b16 v[238:239], v250 offset:47616
	v_exp_f32_e32 v8, v154
	v_exp_f32_e32 v9, v155
	v_exp_f32_e32 v10, v156
	v_exp_f32_e32 v11, v157
	v_exp_f32_e32 v12, v158
	v_exp_f32_e32 v13, v159
	v_exp_f32_e32 v14, v160
	v_exp_f32_e32 v15, v161
	v_cvt_pk_bf16_f32 v182, v8, v9
	v_cvt_pk_bf16_f32 v183, v10, v11
	v_cvt_pk_bf16_f32 v184, v12, v13
	v_cvt_pk_bf16_f32 v185, v14, v15
	v_mfma_f32_32x32x16_bf16 v[162:177], v[78:81], v[126:129], v[162:177]
	ds_read_b64_tr_b16 v[4:5], v250 offset:46144
	s_waitcnt lgkmcnt(11)
	ds_read_b64_tr_b16 v[6:7], v250 offset:47680
	s_xor_b32 s0, s23, 1
	s_mul_i32 s1, s0, 0x4800
	s_mulk_i32 s0, 0x6000
	v_add_u32_e32 v207, s1, v206
	s_waitcnt vmcnt(2)
	ds_write_b128 v207, v[134:137]
	ds_write_b128 v207, v[130:133] offset:16
	v_add_f32_e32 v8, v8, v9
	v_add_f32_e32 v10, v10, v11
	v_add_f32_e32 v12, v12, v13
	v_add_f32_e32 v14, v14, v15
	v_add_f32_e32 v8, v8, v10
	v_add_f32_e32 v12, v12, v14
	v_add_f32_e32 v8, v8, v12
	v_add_f32_e32 v202, v202, v8
	v_cndmask_b32_e64 v182, v182, 0, vcc
	v_cndmask_b32_e64 v183, v183, 0, vcc
	v_cndmask_b32_e64 v184, v184, 0, vcc
	v_cndmask_b32_e64 v185, v185, 0, vcc
	v_mfma_f32_32x32x16_bf16 v[18:33], v[212:215], v[178:181], v[18:33]
	v_add_u32_e32 v207, s0, v208
	s_waitcnt vmcnt(0)
	ds_write_b128 v207, v[142:145] offset:36864
	s_waitcnt lgkmcnt(11)
	ds_write_b128 v207, v[138:141] offset:36880
	v_exp_f32_e32 v8, v162
	v_exp_f32_e32 v9, v163
	v_exp_f32_e32 v10, v164
	v_exp_f32_e32 v11, v165
	v_exp_f32_e32 v12, v166
	v_exp_f32_e32 v13, v167
	v_exp_f32_e32 v14, v168
	v_exp_f32_e32 v15, v169
	v_cvt_pk_bf16_f32 v186, v8, v9
	v_cvt_pk_bf16_f32 v187, v10, v11
	v_cvt_pk_bf16_f32 v188, v12, v13
	v_cvt_pk_bf16_f32 v189, v14, v15
	v_mfma_f32_32x32x16_bf16 v[34:49], v[216:219], v[178:181], v[34:49]
	s_waitcnt lgkmcnt(0)
	s_barrier
	v_add_f32_e32 v8, v8, v9
	v_add_f32_e32 v10, v10, v11
	v_add_f32_e32 v12, v12, v13
	v_add_f32_e32 v14, v14, v15
	v_add_f32_e32 v8, v8, v10
	v_add_f32_e32 v12, v12, v14
	v_add_f32_e32 v8, v8, v12
	v_add_f32_e32 v202, v202, v8
	v_cndmask_b32_e64 v186, v186, 0, vcc
	v_cndmask_b32_e64 v187, v187, 0, vcc
	v_cndmask_b32_e64 v188, v188, 0, vcc
	v_cndmask_b32_e64 v189, v189, 0, vcc
	v_mfma_f32_32x32x16_bf16 v[18:33], v[220:223], v[182:185], v[18:33]
	v_exp_f32_e32 v8, v170
	v_exp_f32_e32 v9, v171
	v_exp_f32_e32 v10, v172
	v_exp_f32_e32 v11, v173
	v_exp_f32_e32 v12, v174
	v_exp_f32_e32 v13, v175
	v_exp_f32_e32 v14, v176
	v_exp_f32_e32 v15, v177
	v_cvt_pk_bf16_f32 v190, v8, v9
	v_cvt_pk_bf16_f32 v191, v10, v11
	v_cvt_pk_bf16_f32 v192, v12, v13
	v_cvt_pk_bf16_f32 v193, v14, v15
	v_mfma_f32_32x32x16_bf16 v[34:49], v[224:227], v[182:185], v[34:49]
	v_add_f32_e32 v8, v8, v9
	v_add_f32_e32 v10, v10, v11
	v_add_f32_e32 v12, v12, v13
	v_add_f32_e32 v14, v14, v15
	v_add_f32_e32 v8, v8, v10
	v_add_f32_e32 v12, v12, v14
	v_add_f32_e32 v8, v8, v12
	v_add_f32_e32 v202, v202, v8
	v_cndmask_b32_e64 v190, v190, 0, vcc
	v_cndmask_b32_e64 v191, v191, 0, vcc
	v_cndmask_b32_e64 v192, v192, 0, vcc
	v_cndmask_b32_e64 v193, v193, 0, vcc
	v_mfma_f32_32x32x16_bf16 v[18:33], v[228:231], v[186:189], v[18:33]
	v_cndmask_b32_e64 v202, v202, 0, vcc
	v_add_f32_e32 v252, v2, v202
	v_mov_b32_e32 v2, v252
	v_mfma_f32_32x32x16_bf16 v[34:49], v[232:235], v[186:189], v[34:49]
	v_mov_b32_e32 v16, v252
	s_nop 1
	s_add_i32 s22, s22, 2
	s_add_i32 s9, s9, 1
	v_add_u32_e32 v246, 0x80, v246
	s_cmp_lt_u32 s9, s17
	s_cselect_b64 s[24:25], -1, 0
	s_cbranch_scc0 .Lnx_a1a
	v_min_i32_e32 v240, 0x1fff, v246
	v_ashrrev_i32_e32 v241, 31, v240
	v_lshlrev_b64 v[240:241], 10, v[240:241]
	v_lshl_add_u64 v[240:241], v[210:211], 0, v[240:241]
	global_load_dwordx4 v[130:133], v[240:241], off offset:16
	global_load_dwordx4 v[134:137], v[240:241], off
	global_load_dwordx4 v[138:141], v[240:241], off offset:528
	global_load_dwordx4 v[142:145], v[240:241], off offset:512

.Latt1b_entry:
	s_lshr_b32 s6, s9, 2
	s_and_b32 s6, s6, 0x3ffffff8
	s_waitcnt lgkmcnt(0)
	v_add3_u32 v251, s1, v205, v204
	v_add_u32_e32 v16, s6, v209
	s_add_i32 s1, s1, s0
	ds_read_b128 v[50:53], v251 offset:9216
	ds_read_b128 v[54:57], v251 offset:9248
	ds_read_b128 v[58:61], v251 offset:9280
	ds_read_b128 v[62:65], v251 offset:9312
	ds_read_b128 v[66:69], v251 offset:13824
	ds_read_b128 v[70:73], v251 offset:13856
	ds_read_b128 v[74:77], v251 offset:13888
	ds_read_b128 v[78:81], v251 offset:13920
	ds_read_b64 v[16:17], v16
	v_add3_u32 v250, s1, v242, v244
	s_waitcnt lgkmcnt(8)
	v_mfma_f32_32x32x16_bf16 v[146:161], v[50:53], v[114:117], 0
	ds_read_b64_tr_b16 v[212:213], v250 offset:49152
	ds_read_b64_tr_b16 v[214:215], v250 offset:50688
	s_waitcnt lgkmcnt(9)
	v_mfma_f32_32x32x16_bf16 v[146:161], v[54:57], v[118:121], v[146:161]
	ds_read_b64_tr_b16 v[216:217], v250 offset:49216
	ds_read_b64_tr_b16 v[218:219], v250 offset:50752
	s_waitcnt lgkmcnt(10)
	v_mfma_f32_32x32x16_bf16 v[146:161], v[58:61], v[122:125], v[146:161]
	ds_read_b64_tr_b16 v[220:221], v250 offset:52224
	ds_read_b64_tr_b16 v[222:223], v250 offset:53760
	s_waitcnt lgkmcnt(11)
	v_mfma_f32_32x32x16_bf16 v[146:161], v[62:65], v[126:129], v[146:161]
	ds_read_b64_tr_b16 v[224:225], v250 offset:52288
	ds_read_b64_tr_b16 v[226:227], v250 offset:53824
	s_waitcnt lgkmcnt(8)
	v_and_b32_e32 v16, s26, v16
	v_and_b32_e32 v17, s27, v17
	v_cmp_eq_u64_e32 vcc, 0, v[16:17]
	s_nop 2
	v_mfma_f32_32x32x16_bf16 v[162:177], v[66:69], v[114:117], 0
	ds_read_b64_tr_b16 v[228:229], v250 offset:55296
	ds_read_b64_tr_b16 v[230:231], v250 offset:56832
	v_exp_f32_e32 v8, v146
	v_exp_f32_e32 v9, v147
	v_exp_f32_e32 v10, v148
	v_exp_f32_e32 v11, v149
	v_exp_f32_e32 v12, v150
	v_exp_f32_e32 v13, v151
	v_exp_f32_e32 v14, v152
	v_exp_f32_e32 v15, v153
	v_cvt_pk_bf16_f32 v178, v8, v9
	v_cvt_pk_bf16_f32 v179, v10, v11
	v_cvt_pk_bf16_f32 v180, v12, v13
	v_mfma_f32_32x32x16_bf16 v[162:177], v[70:73], v[118:121], v[162:177]
	ds_read_b64_tr_b16 v[232:233], v250 offset:55360
	ds_read_b64_tr_b16 v[234:235], v250 offset:56896
	v_cvt_pk_bf16_f32 v181, v14, v15
	v_add_f32_e32 v8, v8, v9
	v_add_f32_e32 v10, v10, v11
	v_add_f32_e32 v12, v12, v13
	v_add_f32_e32 v14, v14, v15
	v_add_f32_e32 v8, v8, v10
	v_add_f32_e32 v12, v12, v14
	v_add_f32_e32 v202, v8, v12
	v_cndmask_b32_e64 v178, v178, 0, vcc
	v_cndmask_b32_e64 v179, v179, 0, vcc
	v_cndmask_b32_e64 v180, v180, 0, vcc
	v_cndmask_b32_e64 v181, v181, 0, vcc
	v_mfma_f32_32x32x16_bf16 v[162:177], v[74:77], v[122:125], v[162:177]
	ds_read_b64_tr_b16 v[236:237], v250 offset:58368
	ds_read_b64_tr_b16 v[238:239], v250 offset:59904
	v_exp_f32_e32 v8, v154
	v_exp_f32_e32 v9, v155
	v_exp_f32_e32 v10, v156
	v_exp_f32_e32 v11, v157
	v_exp_f32_e32 v12, v158
	v_exp_f32_e32 v13, v159
	v_exp_f32_e32 v14, v160
	v_exp_f32_e32 v15, v161
	v_cvt_pk_bf16_f32 v182, v8, v9
	v_cvt_pk_bf16_f32 v183, v10, v11
	v_cvt_pk_bf16_f32 v184, v12, v13
	v_cvt_pk_bf16_f32 v185, v14, v15
	v_mfma_f32_32x32x16_bf16 v[162:177], v[78:81], v[126:129], v[162:177]
	ds_read_b64_tr_b16 v[4:5], v250 offset:58432
	s_waitcnt lgkmcnt(11)
	ds_read_b64_tr_b16 v[6:7], v250 offset:59968
	s_xor_b32 s0, s23, 1
	s_mul_i32 s1, s0, 0x4800
	s_mulk_i32 s0, 0x6000
	v_add_u32_e32 v207, s1, v206
	s_waitcnt vmcnt(2)
	ds_write_b128 v207, v[134:137]
	ds_write_b128 v207, v[130:133] offset:16
	v_add_f32_e32 v8, v8, v9
	v_add_f32_e32 v10, v10, v11
	v_add_f32_e32 v12, v12, v13
	v_add_f32_e32 v14, v14, v15
	v_add_f32_e32 v8, v8, v10
	v_add_f32_e32 v12, v12, v14
	v_add_f32_e32 v8, v8, v12
	v_add_f32_e32 v202, v202, v8
	v_cndmask_b32_e64 v182, v182, 0, vcc
	v_cndmask_b32_e64 v183, v183, 0, vcc
	v_cndmask_b32_e64 v184, v184, 0, vcc
	v_cndmask_b32_e64 v185, v185, 0, vcc
	v_mfma_f32_32x32x16_bf16 v[18:33], v[212:215], v[178:181], v[18:33]
	v_add_u32_e32 v207, s0, v208
	s_waitcnt vmcnt(0)
	ds_write_b128 v207, v[142:145] offset:36864
	s_waitcnt lgkmcnt(11)
	ds_write_b128 v207, v[138:141] offset:36880
	v_exp_f32_e32 v8, v162
	v_exp_f32_e32 v9, v163
	v_exp_f32_e32 v10, v164
	v_exp_f32_e32 v11, v165
	v_exp_f32_e32 v12, v166
	v_exp_f32_e32 v13, v167
	v_exp_f32_e32 v14, v168
	v_exp_f32_e32 v15, v169
	v_cvt_pk_bf16_f32 v186, v8, v9
	v_cvt_pk_bf16_f32 v187, v10, v11
	v_cvt_pk_bf16_f32 v188, v12, v13
	v_cvt_pk_bf16_f32 v189, v14, v15
	v_mfma_f32_32x32x16_bf16 v[34:49], v[216:219], v[178:181], v[34:49]
	s_waitcnt lgkmcnt(0)
	s_barrier
	v_add_f32_e32 v8, v8, v9
	v_add_f32_e32 v10, v10, v11
	v_add_f32_e32 v12, v12, v13
	v_add_f32_e32 v14, v14, v15
	v_add_f32_e32 v8, v8, v10
	v_add_f32_e32 v12, v12, v14
	v_add_f32_e32 v8, v8, v12
	v_add_f32_e32 v202, v202, v8
	v_cndmask_b32_e64 v186, v186, 0, vcc
	v_cndmask_b32_e64 v187, v187, 0, vcc
	v_cndmask_b32_e64 v188, v188, 0, vcc
	v_cndmask_b32_e64 v189, v189, 0, vcc
	v_mfma_f32_32x32x16_bf16 v[18:33], v[220:223], v[182:185], v[18:33]
	v_exp_f32_e32 v8, v170
	v_exp_f32_e32 v9, v171
	v_exp_f32_e32 v10, v172
	v_exp_f32_e32 v11, v173
	v_exp_f32_e32 v12, v174
	v_exp_f32_e32 v13, v175
	v_exp_f32_e32 v14, v176
	v_exp_f32_e32 v15, v177
	v_cvt_pk_bf16_f32 v190, v8, v9
	v_cvt_pk_bf16_f32 v191, v10, v11
	v_cvt_pk_bf16_f32 v192, v12, v13
	v_cvt_pk_bf16_f32 v193, v14, v15
	v_mfma_f32_32x32x16_bf16 v[34:49], v[224:227], v[182:185], v[34:49]
	v_add_f32_e32 v8, v8, v9
	v_add_f32_e32 v10, v10, v11
	v_add_f32_e32 v12, v12, v13
	v_add_f32_e32 v14, v14, v15
	v_add_f32_e32 v8, v8, v10
	v_add_f32_e32 v12, v12, v14
	v_add_f32_e32 v8, v8, v12
	v_add_f32_e32 v202, v202, v8
	v_cndmask_b32_e64 v190, v190, 0, vcc
	v_cndmask_b32_e64 v191, v191, 0, vcc
	v_cndmask_b32_e64 v192, v192, 0, vcc
	v_cndmask_b32_e64 v193, v193, 0, vcc
	v_mfma_f32_32x32x16_bf16 v[18:33], v[228:231], v[186:189], v[18:33]
	v_cndmask_b32_e64 v202, v202, 0, vcc
	v_add_f32_e32 v252, v2, v202
	v_mov_b32_e32 v2, v252
	v_mfma_f32_32x32x16_bf16 v[34:49], v[232:235], v[186:189], v[34:49]
	v_mov_b32_e32 v16, v252
	s_nop 1
	s_add_i32 s22, s22, 2
	s_add_i32 s9, s9, 1
	v_add_u32_e32 v246, 0x80, v246
	s_cmp_lt_u32 s9, s17
	s_cselect_b64 s[24:25], -1, 0
	s_cbranch_scc0 .Lnx_a1b
	v_min_i32_e32 v240, 0x1fff, v246
	v_ashrrev_i32_e32 v241, 31, v240
	v_lshlrev_b64 v[240:241], 10, v[240:241]
	v_lshl_add_u64 v[240:241], v[210:211], 0, v[240:241]
	global_load_dwordx4 v[130:133], v[240:241], off offset:16
	global_load_dwordx4 v[134:137], v[240:241], off
	global_load_dwordx4 v[138:141], v[240:241], off offset:528
	global_load_dwordx4 v[142:145], v[240:241], off offset:512

.Latt2_entry:
	s_lshr_b32 s6, s9, 2
	s_and_b32 s6, s6, 0x3ffffff8
	s_waitcnt lgkmcnt(0)
	v_add3_u32 v251, s1, v205, v204
	v_add_u32_e32 v16, s6, v209
	s_add_i32 s1, s1, s0
	ds_read_b128 v[50:53], v251
	ds_read_b128 v[54:57], v251 offset:32
	ds_read_b128 v[58:61], v251 offset:64
	ds_read_b128 v[62:65], v251 offset:96
	ds_read_b128 v[66:69], v251 offset:4608
	ds_read_b128 v[70:73], v251 offset:4640
	ds_read_b128 v[74:77], v251 offset:4672
	ds_read_b128 v[78:81], v251 offset:4704
	ds_read_b64 v[16:17], v16
	v_add3_u32 v250, s1, v242, v244
	s_waitcnt lgkmcnt(8)
	v_mfma_f32_32x32x16_bf16 v[146:161], v[50:53], v[114:117], 0
	ds_read_b128 v[82:85], v251 offset:9216
	ds_read_b128 v[86:89], v251 offset:9248
	s_waitcnt lgkmcnt(9)
	v_mfma_f32_32x32x16_bf16 v[146:161], v[54:57], v[118:121], v[146:161]
	ds_read_b128 v[90:93], v251 offset:9280
	ds_read_b128 v[94:97], v251 offset:9312
	s_waitcnt lgkmcnt(10)
	v_mfma_f32_32x32x16_bf16 v[146:161], v[58:61], v[122:125], v[146:161]
	ds_read_b128 v[98:101], v251 offset:13824
	ds_read_b128 v[102:105], v251 offset:13856
	s_waitcnt lgkmcnt(11)
	v_mfma_f32_32x32x16_bf16 v[146:161], v[62:65], v[126:129], v[146:161]
	ds_read_b128 v[106:109], v251 offset:13888
	ds_read_b128 v[110:113], v251 offset:13920
	s_waitcnt lgkmcnt(8)
	v_and_b32_e32 v240, s28, v16
	v_and_b32_e32 v241, s29, v17
	v_and_b32_e32 v16, s26, v16
	v_and_b32_e32 v17, s27, v17
	v_cmp_eq_u64_e32 vcc, 0, v[240:241]
	v_cmp_eq_u64_e64 s[6:7], 0, v[16:17]
	v_mfma_f32_32x32x16_bf16 v[162:177], v[66:69], v[114:117], 0
	ds_read_b64_tr_b16 v[212:213], v250 offset:36864
	ds_read_b64_tr_b16 v[214:215], v250 offset:38400
	v_exp_f32_e32 v8, v146
	v_exp_f32_e32 v9, v147
	v_exp_f32_e32 v10, v148
	v_exp_f32_e32 v11, v149
	v_exp_f32_e32 v12, v150
	v_exp_f32_e32 v13, v151
	v_exp_f32_e32 v14, v152
	v_mfma_f32_32x32x16_bf16 v[162:177], v[70:73], v[118:121], v[162:177]
	ds_read_b64_tr_b16 v[216:217], v250 offset:36928
	ds_read_b64_tr_b16 v[218:219], v250 offset:38464
	v_exp_f32_e32 v15, v153
	v_cvt_pk_bf16_f32 v178, v8, v9
	v_cvt_pk_bf16_f32 v179, v10, v11
	v_cvt_pk_bf16_f32 v180, v12, v13
	v_cvt_pk_bf16_f32 v181, v14, v15
	v_add_f32_e32 v8, v8, v9
	v_add_f32_e32 v10, v10, v11
	v_add_f32_e32 v12, v12, v13
	v_mfma_f32_32x32x16_bf16 v[162:177], v[74:77], v[122:125], v[162:177]
	ds_read_b64_tr_b16 v[220:221], v250 offset:39936
	ds_read_b64_tr_b16 v[222:223], v250 offset:41472
	v_add_f32_e32 v14, v14, v15
	v_add_f32_e32 v8, v8, v10
	v_add_f32_e32 v12, v12, v14
	v_add_f32_e32 v202, v8, v12
	v_cndmask_b32_e64 v178, v178, 0, vcc
	v_cndmask_b32_e64 v179, v179, 0, vcc
	v_cndmask_b32_e64 v180, v180, 0, vcc
	v_cndmask_b32_e64 v181, v181, 0, vcc
	v_mfma_f32_32x32x16_bf16 v[162:177], v[78:81], v[126:129], v[162:177]
	ds_read_b64_tr_b16 v[224:225], v250 offset:40000
	s_waitcnt lgkmcnt(11)
	ds_read_b64_tr_b16 v[226:227], v250 offset:41536
	v_exp_f32_e32 v8, v154
	v_exp_f32_e32 v9, v155
	v_exp_f32_e32 v10, v156
	v_exp_f32_e32 v11, v157
	v_exp_f32_e32 v12, v158
	v_exp_f32_e32 v13, v159
	v_exp_f32_e32 v14, v160
	v_exp_f32_e32 v15, v161
	v_mfma_f32_32x32x16_bf16 v[50:65], v[82:85], v[114:117], 0
	ds_read_b64_tr_b16 v[228:229], v250 offset:43008
	ds_read_b64_tr_b16 v[230:231], v250 offset:44544
	v_cvt_pk_bf16_f32 v182, v8, v9
	v_cvt_pk_bf16_f32 v183, v10, v11
	v_cvt_pk_bf16_f32 v184, v12, v13
	v_cvt_pk_bf16_f32 v185, v14, v15
	v_add_f32_e32 v8, v8, v9
	v_add_f32_e32 v10, v10, v11
	v_add_f32_e32 v12, v12, v13
	v_add_f32_e32 v14, v14, v15
	v_mfma_f32_32x32x16_bf16 v[50:65], v[86:89], v[118:121], v[50:65]
	ds_read_b64_tr_b16 v[232:233], v250 offset:43072
	s_waitcnt lgkmcnt(11)
	ds_read_b64_tr_b16 v[234:235], v250 offset:44608
	v_add_f32_e32 v8, v8, v10
	v_add_f32_e32 v12, v12, v14
	v_add_f32_e32 v8, v8, v12
	v_add_f32_e32 v202, v202, v8
	v_cndmask_b32_e64 v182, v182, 0, vcc
	v_cndmask_b32_e64 v183, v183, 0, vcc
	v_cndmask_b32_e64 v184, v184, 0, vcc
	v_cndmask_b32_e64 v185, v185, 0, vcc
	v_mfma_f32_32x32x16_bf16 v[50:65], v[90:93], v[122:125], v[50:65]
	ds_read_b64_tr_b16 v[236:237], v250 offset:46080
	ds_read_b64_tr_b16 v[238:239], v250 offset:47616
	ds_read_b64_tr_b16 v[146:147], v250 offset:49152
	s_waitcnt lgkmcnt(11)
	ds_read_b64_tr_b16 v[148:149], v250 offset:50688
	v_exp_f32_e32 v8, v162
	v_exp_f32_e32 v9, v163
	v_exp_f32_e32 v10, v164
	v_exp_f32_e32 v11, v165
	v_exp_f32_e32 v12, v166
	v_exp_f32_e32 v13, v167
	v_exp_f32_e32 v14, v168
	v_exp_f32_e32 v15, v169
	v_mfma_f32_32x32x16_bf16 v[50:65], v[94:97], v[126:129], v[50:65]
	ds_read_b64_tr_b16 v[4:5], v250 offset:46144
	ds_read_b64_tr_b16 v[6:7], v250 offset:47680
	ds_read_b64_tr_b16 v[150:151], v250 offset:49216
	s_waitcnt lgkmcnt(11)
	ds_read_b64_tr_b16 v[152:153], v250 offset:50752
	v_cvt_pk_bf16_f32 v186, v8, v9
	v_cvt_pk_bf16_f32 v187, v10, v11
	v_cvt_pk_bf16_f32 v188, v12, v13
	v_cvt_pk_bf16_f32 v189, v14, v15
	v_add_f32_e32 v8, v8, v9
	v_add_f32_e32 v10, v10, v11
	v_add_f32_e32 v12, v12, v13
	v_add_f32_e32 v14, v14, v15
	v_mfma_f32_32x32x16_bf16 v[66:81], v[98:101], v[114:117], 0
	ds_read_b64_tr_b16 v[154:155], v250 offset:52224
	ds_read_b64_tr_b16 v[156:157], v250 offset:53760
	ds_read_b64_tr_b16 v[82:83], v250 offset:55296
	s_waitcnt lgkmcnt(11)
	ds_read_b64_tr_b16 v[84:85], v250 offset:56832
	v_add_f32_e32 v8, v8, v10
	v_add_f32_e32 v12, v12, v14
	v_add_f32_e32 v8, v8, v12
	v_add_f32_e32 v202, v202, v8
	v_cndmask_b32_e64 v186, v186, 0, vcc
	v_cndmask_b32_e64 v187, v187, 0, vcc
	v_cndmask_b32_e64 v188, v188, 0, vcc
	v_cndmask_b32_e64 v189, v189, 0, vcc
	v_mfma_f32_32x32x16_bf16 v[66:81], v[102:105], v[118:121], v[66:81]
	ds_read_b64_tr_b16 v[158:159], v250 offset:52288
	ds_read_b64_tr_b16 v[160:161], v250 offset:53824
	ds_read_b64_tr_b16 v[86:87], v250 offset:55360
	s_waitcnt lgkmcnt(11)
	ds_read_b64_tr_b16 v[88:89], v250 offset:56896
	v_exp_f32_e32 v8, v170
	v_exp_f32_e32 v9, v171
	v_exp_f32_e32 v10, v172
	v_exp_f32_e32 v11, v173
	v_exp_f32_e32 v12, v174
	v_exp_f32_e32 v13, v175
	v_exp_f32_e32 v14, v176
	v_exp_f32_e32 v15, v177
	v_mfma_f32_32x32x16_bf16 v[66:81], v[106:109], v[122:125], v[66:81]
	ds_read_b64_tr_b16 v[90:91], v250 offset:58368
	ds_read_b64_tr_b16 v[92:93], v250 offset:59904
	s_xor_b32 s0, s23, 1
	s_mul_i32 s1, s0, 0x4800
	s_mulk_i32 s0, 0x6000
	v_add_u32_e32 v207, s1, v206
	s_waitcnt vmcnt(2)
	ds_write_b128 v207, v[134:137]
	s_waitcnt lgkmcnt(11)
	ds_write_b128 v207, v[130:133] offset:16
	v_cvt_pk_bf16_f32 v190, v8, v9
	v_cvt_pk_bf16_f32 v191, v10, v11
	v_cvt_pk_bf16_f32 v192, v12, v13
	v_cvt_pk_bf16_f32 v193, v14, v15
	v_add_f32_e32 v8, v8, v9
	v_add_f32_e32 v10, v10, v11
	v_add_f32_e32 v12, v12, v13
	v_add_f32_e32 v14, v14, v15
	v_mfma_f32_32x32x16_bf16 v[66:81], v[110:113], v[126:129], v[66:81]
	ds_read_b64_tr_b16 v[94:95], v250 offset:58432
	ds_read_b64_tr_b16 v[96:97], v250 offset:59968
	v_add_u32_e32 v207, s0, v208
	s_waitcnt vmcnt(0)
	ds_write_b128 v207, v[142:145] offset:36864
	s_waitcnt lgkmcnt(11)
	ds_write_b128 v207, v[138:141] offset:36880
	v_add_f32_e32 v8, v8, v10
	v_add_f32_e32 v12, v12, v14
	v_add_f32_e32 v8, v8, v12
	v_add_f32_e32 v202, v202, v8
	v_cndmask_b32_e64 v190, v190, 0, vcc
	v_cndmask_b32_e64 v191, v191, 0, vcc
	v_cndmask_b32_e64 v192, v192, 0, vcc
	v_cndmask_b32_e64 v193, v193, 0, vcc
	v_mfma_f32_32x32x16_bf16 v[18:33], v[212:215], v[178:181], v[18:33]
	s_waitcnt lgkmcnt(0)
	s_barrier
	v_exp_f32_e32 v8, v50
	v_exp_f32_e32 v9, v51
	v_exp_f32_e32 v10, v52
	v_exp_f32_e32 v11, v53
	v_exp_f32_e32 v12, v54
	v_exp_f32_e32 v13, v55
	v_exp_f32_e32 v14, v56
	v_exp_f32_e32 v15, v57
	v_mfma_f32_32x32x16_bf16 v[34:49], v[216:219], v[178:181], v[34:49]
	v_cvt_pk_bf16_f32 v178, v8, v9
	v_cvt_pk_bf16_f32 v179, v10, v11
	v_cvt_pk_bf16_f32 v180, v12, v13
	v_cvt_pk_bf16_f32 v181, v14, v15
	v_add_f32_e32 v8, v8, v9
	v_add_f32_e32 v10, v10, v11
	v_add_f32_e32 v12, v12, v13
	v_add_f32_e32 v14, v14, v15
	v_mfma_f32_32x32x16_bf16 v[18:33], v[220:223], v[182:185], v[18:33]
	v_add_f32_e32 v8, v8, v10
	v_add_f32_e32 v12, v12, v14
	v_add_f32_e32 v203, v8, v12
	v_cndmask_b32_e64 v178, v178, 0, s[6:7]
	v_cndmask_b32_e64 v179, v179, 0, s[6:7]
	v_cndmask_b32_e64 v180, v180, 0, s[6:7]
	v_cndmask_b32_e64 v181, v181, 0, s[6:7]
	v_exp_f32_e32 v8, v58
	v_mfma_f32_32x32x16_bf16 v[34:49], v[224:227], v[182:185], v[34:49]
	v_exp_f32_e32 v9, v59
	v_exp_f32_e32 v10, v60
	v_exp_f32_e32 v11, v61
	v_exp_f32_e32 v12, v62
	v_exp_f32_e32 v13, v63
	v_exp_f32_e32 v14, v64
	v_exp_f32_e32 v15, v65
	v_cvt_pk_bf16_f32 v182, v8, v9
	v_mfma_f32_32x32x16_bf16 v[18:33], v[228:231], v[186:189], v[18:33]
	v_cvt_pk_bf16_f32 v183, v10, v11
	v_cvt_pk_bf16_f32 v184, v12, v13
	v_cvt_pk_bf16_f32 v185, v14, v15
	v_add_f32_e32 v8, v8, v9
	v_add_f32_e32 v10, v10, v11
	v_add_f32_e32 v12, v12, v13
	v_add_f32_e32 v14, v14, v15
	v_add_f32_e32 v8, v8, v10
	v_mfma_f32_32x32x16_bf16 v[34:49], v[232:235], v[186:189], v[34:49]
	v_add_f32_e32 v12, v12, v14
	v_add_f32_e32 v8, v8, v12
	v_add_f32_e32 v203, v203, v8
	v_cndmask_b32_e64 v182, v182, 0, s[6:7]
	v_cndmask_b32_e64 v183, v183, 0, s[6:7]
	v_cndmask_b32_e64 v184, v184, 0, s[6:7]
	v_cndmask_b32_e64 v185, v185, 0, s[6:7]
	v_exp_f32_e32 v8, v66
	v_mfma_f32_32x32x16_bf16 v[18:33], v[236:239], v[190:193], v[18:33]
	v_exp_f32_e32 v9, v67
	v_exp_f32_e32 v10, v68
	v_exp_f32_e32 v11, v69
	v_exp_f32_e32 v12, v70
	v_exp_f32_e32 v13, v71
	v_exp_f32_e32 v14, v72
	v_exp_f32_e32 v15, v73
	v_cvt_pk_bf16_f32 v186, v8, v9
	v_mfma_f32_32x32x16_bf16 v[34:49], v[4:7], v[190:193], v[34:49]
	v_cvt_pk_bf16_f32 v187, v10, v11
	v_cvt_pk_bf16_f32 v188, v12, v13
	v_cvt_pk_bf16_f32 v189, v14, v15
	v_add_f32_e32 v8, v8, v9
	v_add_f32_e32 v10, v10, v11
	v_add_f32_e32 v12, v12, v13
	v_add_f32_e32 v14, v14, v15
	v_add_f32_e32 v8, v8, v10
	v_mfma_f32_32x32x16_bf16 v[18:33], v[146:149], v[178:181], v[18:33]
	v_add_f32_e32 v12, v12, v14
	v_add_f32_e32 v8, v8, v12
	v_add_f32_e32 v203, v203, v8
	v_cndmask_b32_e64 v186, v186, 0, s[6:7]
	v_cndmask_b32_e64 v187, v187, 0, s[6:7]
	v_cndmask_b32_e64 v188, v188, 0, s[6:7]
	v_cndmask_b32_e64 v189, v189, 0, s[6:7]
	v_exp_f32_e32 v8, v74
	v_mfma_f32_32x32x16_bf16 v[34:49], v[150:153], v[178:181], v[34:49]
	v_exp_f32_e32 v9, v75
	v_exp_f32_e32 v10, v76
	v_exp_f32_e32 v11, v77
	v_exp_f32_e32 v12, v78
	v_exp_f32_e32 v13, v79
	v_exp_f32_e32 v14, v80
	v_exp_f32_e32 v15, v81
	v_cvt_pk_bf16_f32 v190, v8, v9
	v_mfma_f32_32x32x16_bf16 v[18:33], v[154:157], v[182:185], v[18:33]
	v_cvt_pk_bf16_f32 v191, v10, v11
	v_cvt_pk_bf16_f32 v192, v12, v13
	v_cvt_pk_bf16_f32 v193, v14, v15
	v_add_f32_e32 v8, v8, v9
	v_add_f32_e32 v10, v10, v11
	v_add_f32_e32 v12, v12, v13
	v_add_f32_e32 v14, v14, v15
	v_add_f32_e32 v8, v8, v10
	v_mfma_f32_32x32x16_bf16 v[34:49], v[158:161], v[182:185], v[34:49]
	v_add_f32_e32 v12, v12, v14
	v_add_f32_e32 v8, v8, v12
	v_add_f32_e32 v203, v203, v8
	v_cndmask_b32_e64 v190, v190, 0, s[6:7]
	v_cndmask_b32_e64 v191, v191, 0, s[6:7]
	v_cndmask_b32_e64 v192, v192, 0, s[6:7]
	v_cndmask_b32_e64 v193, v193, 0, s[6:7]
	v_cndmask_b32_e64 v202, v202, 0, vcc
	v_mfma_f32_32x32x16_bf16 v[18:33], v[82:85], v[186:189], v[18:33]
	v_cndmask_b32_e64 v203, v203, 0, s[6:7]
	v_add_f32_e32 v202, v202, v203
	v_add_f32_e32 v252, v2, v202
	v_mov_b32_e32 v2, v252
	s_add_i32 s22, s22, 2
	s_add_i32 s9, s9, 1
	v_add_u32_e32 v246, 0x80, v246
	s_cmp_lt_u32 s9, s17
	s_cselect_b64 s[24:25], -1, 0
	s_cbranch_scc0 .Lnx_a2
	v_min_i32_e32 v240, 0x1fff, v246
	v_ashrrev_i32_e32 v241, 31, v240
	v_lshlrev_b64 v[240:241], 10, v[240:241]
	v_lshl_add_u64 v[240:241], v[210:211], 0, v[240:241]
	global_load_dwordx4 v[130:133], v[240:241], off offset:16
	global_load_dwordx4 v[134:137], v[240:241], off
	global_load_dwordx4 v[138:141], v[240:241], off offset:528
	global_load_dwordx4 v[142:145], v[240:241], off offset:512
.Lnx_a2:
	v_mfma_f32_32x32x16_bf16 v[34:49], v[86:89], v[186:189], v[34:49]
	v_mov_b32_e32 v4, v252
	s_nop 1
	v_permlane32_swap_b32_e32 v2, v4
	s_add_i32 s23, s22, 1
	s_cmp_lt_u32 s9, 32
	s_mov_b32 s6, 62
	s_cselect_b32 s1, s33, s16
	s_cselect_b32 s0, s37, s8
	s_cmp_ge_u32 s23, s20
	s_mov_b32 s7, 63
	s_cselect_b64 s[10:11], -1, 0
	s_and_b64 s[6:7], s[22:23], s[6:7]
	s_lshl_b64 s[28:29], 1, s6
	s_lshl_b64 s[26:27], 1, s7
	s_and_b64 s[6:7], s[28:29], s[0:1]
	v_mfma_f32_32x32x16_bf16 v[18:33], v[90:93], v[190:193], v[18:33]
	v_max_f32_e32 v4, v4, v4
	s_cmp_eq_u64 s[6:7], 0
	s_cselect_b64 vcc, -1, 0
	s_and_b64 s[34:35], s[26:27], s[0:1]
	s_cmp_eq_u64 s[34:35], 0
	s_cselect_b64 s[0:1], -1, 0
	s_or_b64 s[0:1], vcc, s[0:1]
	s_or_b64 s[0:1], s[0:1], s[10:11]
	v_mfma_f32_32x32x16_bf16 v[34:49], v[94:97], v[190:193], v[34:49]
	v_max_f32_e32 v2, v2, v2
	v_max_f32_e32 v2, v2, v4
	v_cmp_lt_f32_e32 vcc, s15, v2
	s_cbranch_vccnz .Lsel_shift_h
	s_cmp_eq_u32 s31, s22
	s_cbranch_scc1 .Lsel_fast_exit
	v_mov_b32_e32 v2, v252
	s_and_b32 s23, s9, 1
	s_cmp_eq_u64 s[0:1], 0
	s_mul_i32 s1, s23, 0x4800
	s_mul_i32 s0, s23, 0x1800
	s_cbranch_scc1 .Latt2_entry
	s_cmp_lg_u64 s[10:11], 0
	s_cbranch_scc1 .Lsel_generic
	s_cmp_lg_u64 s[6:7], 0
	s_cbranch_scc1 .Latt1a_entry
	s_cmp_lg_u64 s[34:35], 0
	s_cbranch_scc1 .Latt1b_entry
	s_branch .Lsel_none
